# GEMM loops: per-segment setprio flips removed, one static setprio 1 for waves 0-3 per GEMM phase
# baseline (speedup 1.0000x reference)
.LBB0_136:
	s_or_b64 exec, exec, s[4:5]
	s_xor_b64 s[0:1], s[0:1], -1
	v_writelane_b32 v253, s0, 28
	s_waitcnt lgkmcnt(0)
	v_mov_b32_e32 v0, v179
	v_writelane_b32 v253, s1, 29
	v_readlane_b32 s0, v250, 51
	v_readlane_b32 s1, v250, 52
	s_barrier
	s_nop 0
	v_cndmask_b32_e64 v1, 0, 1, s[0:1]
	v_cmp_ne_u32_e64 s[4:5], 1, v1
	s_andn2_b64 vcc, exec, s[0:1]
	v_readfirstlane_b32 s0, v0
	v_writelane_b32 v253, s4, 30
	s_nop 1
	v_writelane_b32 v253, s5, 31
	s_cbranch_vccnz .LBB0_152
	v_readfirstlane_b32 s100, v179
	s_lshr_b32 s100, s100, 6
	s_cmp_lt_u32 s100, 4
	s_cbranch_scc0 .Lprio_done0
	s_setprio 1

.LBB0_204:
	s_or_b64 exec, exec, s[0:1]
	v_readlane_b32 s0, v250, 53
	v_readlane_b32 s1, v250, 54
	v_mov_b32_e32 v8, v179
	s_waitcnt lgkmcnt(0)
	v_cndmask_b32_e64 v0, 0, 1, s[0:1]
	s_barrier
	v_cmp_ne_u32_e64 s[74:75], 1, v0
	s_andn2_b64 vcc, exec, s[0:1]
	v_readfirstlane_b32 s0, v8
	s_cbranch_vccnz .LBB0_228
	v_readfirstlane_b32 s100, v179
	s_lshr_b32 s100, s100, 6
	s_cmp_lt_u32 s100, 4
	s_cbranch_scc0 .Lprio_done1
	s_setprio 1

.LBB0_352:
	s_or_b64 exec, exec, s[0:1]
	v_readlane_b32 s0, v250, 57
	v_mov_b32_e32 v6, v179
	v_readlane_b32 s1, v250, 58
	s_waitcnt lgkmcnt(0)
	s_barrier
	s_andn2_b64 vcc, exec, s[0:1]
	v_readfirstlane_b32 s0, v6
	s_cbranch_vccnz .LBB0_368
	v_readfirstlane_b32 s100, v179
	s_lshr_b32 s100, s100, 6
	s_cmp_lt_u32 s100, 4
	s_cbranch_scc0 .Lprio_done2
	s_setprio 1

.LBB0_957:
	s_or_b64 exec, exec, s[0:1]
	v_mov_b32_e32 v8, v179
	s_waitcnt lgkmcnt(0)
	s_barrier
	s_and_b64 vcc, exec, s[74:75]
	v_readfirstlane_b32 s0, v8
	s_cbranch_vccnz .LBB0_977
	v_readfirstlane_b32 s100, v179
	s_lshr_b32 s100, s100, 6
	s_cmp_lt_u32 s100, 4
	s_cbranch_scc0 .Lprio_done3
	s_setprio 1

.LBB0_1087:
	s_or_b64 exec, exec, s[0:1]
	v_readlane_b32 s0, v253, 30
	v_mov_b32_e32 v6, v179
	v_readlane_b32 s1, v253, 31
	s_waitcnt lgkmcnt(0)
	s_barrier
	s_and_b64 vcc, exec, s[0:1]
	v_readfirstlane_b32 s0, v6
	s_cbranch_vccnz .LBB0_1103
	v_readfirstlane_b32 s100, v179
	s_lshr_b32 s100, s100, 6
	s_cmp_lt_u32 s100, 4
	s_cbranch_scc0 .Lprio_done4
	s_setprio 1
